# prompt attention: V tile also staged through LDS (linear copy, ds_read_b64 fragments), second barrier moved after all LDS reads
# speedup vs baseline: 1.0146x; 1.0064x over previous
; __device__ __forceinline__ void attn_prompt_wave(const Params& P, int l, int qt, int tid_in) {
;     ...
;     const int q0 = qt * 32, key0 = q0 - 128;
;     bf16x8 qf[4];
; #pragma unroll
;     for (int kk = 0; kk < 4; ++kk) qf[kk] = *(const bf16x8*)(Q + (size_t)(q0 + l32) * 512 + head * 64 + kk * 16 + h * 8);
;     bf16x8 kf[5][4];
; #pragma unroll
;     for (int kb = 0; kb < 5; ++kb) {
;         int krow_ = key0 + kb * 32 + l32; krow_ = krow_ < 0 ? 0 : krow_;
;         const bf16* kp = KB + (size_t)krow_ * 128 + kvh * 64 + h * 8;
; #pragma unroll
;         for (int kk = 0; kk < 4; ++kk) kf[kb][kk] = *(const bf16x8*)(kp + kk * 16);
;     }
;     u32x2 vfa[5][2][2], vfb[5][2][2];
; #pragma unroll
;     for (int kb = 0; kb < 5; ++kb)
; #pragma unroll
;         for (int s = 0; s < 2; ++s) {
;             int k0 = key0 + kb * 32 + 16 * s + 4 * h, k1 = k0 + 8; k0 = k0 < 0 ? 0 : k0; k1 = k1 < 0 ? 0 : k1;
; #pragma unroll
;             for (int db = 0; db < 2; ++db) {
;                 const bf16* vp = VT + ((size_t)kvh * (MP / 4) * 64 + db * 32 + l32) * 4;
;                 vfa[kb][s][db] = *(const u32x2*)(vp + (size_t)(k0 >> 2) * 256); vfb[kb][s][db] = *(const u32x2*)(vp + (size_t)(k1 >> 2) * 256);
.LBB0_1019:
	s_and_b64 vcc, exec, s[0:1]
	s_cbranch_vccz .LBB0_953
	s_lshl_b32 s0, s14, 5
	v_readlane_b32 s2, v254, 0
	v_readlane_b32 s3, v254, 1
	v_readlane_b32 s18, v254, 2
	v_readlane_b32 s19, v254, 3
	v_and_b32_e32 v72, 7, v216
	v_bfe_u32 v73, v216, 3, 5
	v_ashrrev_i32_e32 v74, 8, v216
	v_lshlrev_b32_e32 v75, 4, v72
	s_addk_i32 s0, 0xff80
	v_lshl_or_b32 v75, v74, 7, v75
	v_add_u32_e32 v64, s0, v73
	v_mul_u32_u24_e32 v68, 0x90, v73
	v_mul_u32_u24_e32 v73, 0x5a00, v74
	v_lshl_add_u32 v68, v72, 4, v68
	v_add_u32_e32 v68, v68, v73
	v_max_i32_e32 v65, 0, v64
	v_lshl_add_u32 v65, v65, 8, v75
	global_load_dwordx4 v[28:31], v65, s[2:3]
	v_add_u32_e32 v65, 32, v64
	v_max_i32_e32 v65, 0, v65
	v_lshl_add_u32 v65, v65, 8, v75
	global_load_dwordx4 v[24:27], v65, s[2:3]
	v_add_u32_e32 v65, 64, v64
	v_max_i32_e32 v65, 0, v65
	v_lshl_add_u32 v65, v65, 8, v75
	global_load_dwordx4 v[16:19], v65, s[2:3]
	v_add_u32_e32 v65, 96, v64
	v_max_i32_e32 v65, 0, v65
	v_lshl_add_u32 v65, v65, 8, v75
	global_load_dwordx4 v[20:23], v65, s[2:3]
	v_add_u32_e32 v65, 128, v64
	v_max_i32_e32 v65, 0, v65
	v_lshl_add_u32 v65, v65, 8, v75
	global_load_dwordx4 v[76:79], v65, s[2:3]
	s_lshl_b32 s1, s14, 3
	v_bfe_u32 v72, v216, 5, 3
	v_and_b32_e32 v73, 31, v216
	s_sub_i32 s1, s1, 32
	v_mul_u32_u24_e32 v75, 0x218000, v74
	v_lshlrev_b32_e32 v73, 4, v73
	v_add_u32_e32 v72, s1, v72
	v_add_u32_e32 v73, v73, v75
	v_and_b32_e32 v201, 0xff, v216
	v_mul_u32_u24_e32 v75, 0x5000, v74
	v_lshlrev_b32_e32 v201, 4, v201
	v_add_u32_e32 v75, 0xb400, v75
	v_add_u32_e32 v201, v201, v75
	v_bfe_u32 v200, v216, 5, 1
	v_and_b32_e32 v66, 31, v216
	v_lshlrev_b32_e32 v200, 9, v200
	v_lshl_add_u32 v200, v66, 3, v200
	v_add_u32_e32 v200, v200, v75
	v_max_i32_e32 v65, 0, v72
	v_lshl_add_u32 v65, v65, 9, v73
	global_load_dwordx4 v[204:207], v65, s[18:19]
	v_add_u32_e32 v65, 8, v72
	v_max_i32_e32 v65, 0, v65
	v_lshl_add_u32 v65, v65, 9, v73
	global_load_dwordx4 v[208:211], v65, s[18:19]
	v_add_u32_e32 v65, 16, v72
	v_max_i32_e32 v65, 0, v65
	v_lshl_add_u32 v65, v65, 9, v73
	global_load_dwordx4 v[212:215], v65, s[18:19]
	v_add_u32_e32 v65, 24, v72
	v_max_i32_e32 v65, 0, v65
	v_lshl_add_u32 v65, v65, 9, v73
	global_load_dwordx4 v[234:237], v65, s[18:19]
	v_add_u32_e32 v65, 32, v72
	v_max_i32_e32 v65, 0, v65
	v_lshl_add_u32 v65, v65, 9, v73
	global_load_dwordx4 v[238:241], v65, s[18:19]
	v_mov_b32_e32 v10, v216
	s_lshl_b32 s0, s14, 5
	v_and_b32_e32 v11, 31, v10
	v_ashrrev_i32_e32 v13, 8, v10
	v_or_b32_e32 v182, s0, v11
	v_lshlrev_b32_e32 v0, 6, v13
	v_readlane_b32 s2, v254, 0
	v_bfe_u32 v12, v10, 5, 1
	v_ashrrev_i32_e32 v183, 31, v182
	v_readlane_b32 s36, v252, 1
	s_add_i32 s1, s0, 0xffffff80
	v_ashrrev_i32_e32 v1, 31, v0
	v_readlane_b32 s3, v254, 1
	v_lshlrev_b64 v[178:179], 10, v[182:183]
	v_readlane_b32 s38, v252, 3
	v_readlane_b32 s39, v252, 4
	v_lshlrev_b32_e32 v80, 4, v12
	v_lshl_add_u64 v[0:1], v[0:1], 1, s[2:3]
	s_cmp_lt_i32 s14, 4
	v_lshl_add_u64 v[4:5], s[38:39], 0, v[178:179]
	v_lshl_add_u64 v[6:7], v[0:1], 0, v[80:81]
	v_or_b32_e32 v0, s1, v11
	s_cselect_b64 s[38:39], -1, 0
	v_cndmask_b32_e64 v0, v0, 0, s[38:39]
	v_ashrrev_i32_e32 v1, 31, v0
	v_lshlrev_b64 v[0:1], 8, v[0:1]
	v_lshl_add_u64 v[8:9], v[6:7], 0, v[0:1]
	v_and_b32_e32 v180, 0xffffffc0, v10
	v_ashrrev_i32_e32 v181, 31, v180
	v_lshl_add_u64 v[4:5], v[180:181], 1, v[4:5]
	v_lshl_add_u64 v[4:5], v[4:5], 0, v[80:81]
	global_load_dwordx4 v[32:35], v[4:5], off
	global_load_dwordx4 v[90:93], v[4:5], off offset:32
	global_load_dwordx4 v[166:169], v[4:5], off offset:64
	global_load_dwordx4 v[162:165], v[4:5], off offset:96
	s_add_i32 s17, s0, 0xffffffa0
	v_readlane_b32 s37, v252, 2
	s_cmp_lt_i32 s14, 3
	v_or_b32_e32 v4, s17, v11
	s_cselect_b64 s[36:37], -1, 0
	v_cndmask_b32_e64 v4, v4, 0, s[36:37]
	v_ashrrev_i32_e32 v5, 31, v4
	v_lshlrev_b64 v[4:5], 8, v[4:5]
	v_lshl_add_u64 v[4:5], v[6:7], 0, v[4:5]
	s_sub_i32 s16, s0, 64
	s_cmp_lt_i32 s14, 2
	v_or_b32_e32 v4, s16, v11
	s_cselect_b64 s[8:9], -1, 0
	v_cndmask_b32_e64 v4, v4, 0, s[8:9]
	v_ashrrev_i32_e32 v5, 31, v4
	v_lshlrev_b64 v[4:5], 8, v[4:5]
	v_lshl_add_u64 v[4:5], v[6:7], 0, v[4:5]
	s_sub_i32 s15, s0, 32
	s_cmp_lt_i32 s14, 1
	v_or_b32_e32 v4, s15, v11
	s_cselect_b64 s[4:5], -1, 0
	v_cndmask_b32_e64 v4, v4, 0, s[4:5]
	v_ashrrev_i32_e32 v5, 31, v4
	v_lshlrev_b64 v[4:5], 8, v[4:5]
	s_cmp_lt_i32 s14, 0
	v_lshl_add_u64 v[4:5], v[6:7], 0, v[4:5]
	s_cselect_b64 s[2:3], -1, 0
	v_cndmask_b32_e64 v4, v182, 0, s[2:3]
	v_ashrrev_i32_e32 v5, 31, v4
	v_lshlrev_b64 v[4:5], 8, v[4:5]
	v_lshl_add_u64 v[4:5], v[6:7], 0, v[4:5]
	v_lshlrev_b32_e32 v80, 2, v12
	v_mul_i32_i24_e32 v4, 0x43000, v13
	v_readlane_b32 s18, v254, 2
	v_or_b32_e32 v183, s1, v80
	v_mul_hi_i32_i24_e32 v5, 0x43000, v13
	v_or_b32_e32 v4, v4, v11
	v_readlane_b32 s19, v254, 3
	v_ashrrev_i32_e32 v104, 2, v183
	v_or_b32_e32 v6, 2, v104
	v_lshl_add_u64 v[184:185], v[4:5], 3, s[18:19]
	v_cndmask_b32_e64 v4, v104, 0, s[38:39]
	v_ashrrev_i32_e32 v5, 31, v4
	v_cndmask_b32_e64 v6, v6, 0, s[38:39]
	v_lshlrev_b64 v[4:5], 9, v[4:5]
	v_ashrrev_i32_e32 v7, 31, v6
	v_lshlrev_b64 v[6:7], 9, v[6:7]
	v_lshl_add_u64 v[4:5], v[184:185], 0, v[4:5]
	v_lshl_add_u64 v[6:7], v[184:185], 0, v[6:7]
	v_or_b32_e32 v4, 4, v104
	v_ashrrev_i32_e32 v190, 6, v10
	v_cndmask_b32_e64 v102, v4, 0, s[38:39]
	v_or_b32_e32 v104, 6, v104
	v_cndmask_b32_e64 v104, v104, 0, s[38:39]
	s_waitcnt vmcnt(4)
	ds_write_b128 v68, v[28:31]
	ds_write_b128 v68, v[24:27] offset:4608
	ds_write_b128 v68, v[16:19] offset:9216
	ds_write_b128 v68, v[20:23] offset:13824
	ds_write_b128 v68, v[76:79] offset:18432
	ds_write_b128 v201, v[204:207]
	ds_write_b128 v201, v[208:211] offset:4096
	ds_write_b128 v201, v[212:215] offset:8192
	ds_write_b128 v201, v[234:237] offset:12288
	ds_write_b128 v201, v[238:241] offset:16384
	v_and_b32_e32 v170, 31, v216
	v_bfe_u32 v171, v216, 5, 1
	v_mul_u32_u24_e32 v170, 0x90, v170
	v_ashrrev_i32_e32 v172, 8, v216
	v_lshl_add_u32 v170, v171, 4, v170
	v_mul_u32_u24_e32 v172, 0x5a00, v172
	s_nop 0
	v_add_u32_e32 v170, v170, v172
	s_waitcnt lgkmcnt(0)
	s_barrier
; #define MFMA32(a, b, c) __builtin_amdgcn_mfma_f32_32x32x16_bf16((a), (b), (c), 0, 0, 0)
; __device__ __forceinline__ void attn_prompt_wave(const Params& P, int l, int qt, int tid_in) {
;     ...
;     u32x2 vfa[5][2][2], vfb[5][2][2];
; #pragma unroll
;     for (int kb = 0; kb < 5; ++kb)
; #pragma unroll
;         for (int s = 0; s < 2; ++s) {
;             int k0 = key0 + kb * 32 + 16 * s + 4 * h, k1 = k0 + 8; k0 = k0 < 0 ? 0 : k0; k1 = k1 < 0 ? 0 : k1;
; #pragma unroll
;             for (int db = 0; db < 2; ++db) {
;                 const bf16* vp = VT + ((size_t)kvh * (MP / 4) * 64 + db * 32 + l32) * 4;
;                 vfa[kb][s][db] = *(const u32x2*)(vp + (size_t)(k0 >> 2) * 256); vfb[kb][s][db] = *(const u32x2*)(vp + (size_t)(k1 >> 2) * 256);
;             }
;         }
;     f32x16 st[5];
; #pragma unroll
;     for (int kb = 0; kb < 5; ++kb) {
; #pragma unroll
;         for (int i = 0; i < 16; ++i) st[kb][i] = 0.f;
; #pragma unroll
;         for (int kk = 0; kk < 4; ++kk) st[kb] = MFMA32(kf[kb][kk], qf[kk], st[kb]);
;     }
	ds_read_b128 v[0:3], v170
	ds_read_b128 v[28:31], v170 offset:32
	ds_read_b128 v[24:27], v170 offset:64
	ds_read_b128 v[16:19], v170 offset:96
	ds_read_b128 v[20:23], v170 offset:4608
	ds_read_b128 v[76:79], v170 offset:4640
	ds_read_b128 v[72:75], v170 offset:4672
	ds_read_b128 v[64:67], v170 offset:4704
	ds_read_b128 v[68:71], v170 offset:9216
	ds_read_b128 v[60:63], v170 offset:9248
	ds_read_b128 v[56:59], v170 offset:9280
	ds_read_b128 v[48:51], v170 offset:9312
	ds_read_b128 v[52:55], v170 offset:13824
	ds_read_b128 v[98:101], v170 offset:13856
	ds_read_b128 v[44:47], v170 offset:13888
	ds_read_b128 v[36:39], v170 offset:13920
	ds_read_b128 v[40:43], v170 offset:18432
	ds_read_b128 v[94:97], v170 offset:18464
	ds_read_b128 v[174:177], v170 offset:18496
	ds_read_b128 v[170:173], v170 offset:18528
	ds_read_b64 v[86:87], v200
	ds_read_b64 v[88:89], v200 offset:1024
	ds_read_b64 v[84:85], v200 offset:1280
	ds_read_b64 v[82:83], v200 offset:256
	s_waitcnt vmcnt(3)
	s_waitcnt lgkmcnt(4)
	v_mfma_f32_32x32x16_bf16 v[0:15], v[0:3], v[32:35], 0
	v_ashrrev_i32_e32 v103, 31, v102
	v_ashrrev_i32_e32 v105, 31, v104
	v_lshlrev_b64 v[102:103], 9, v[102:103]
	v_lshlrev_b64 v[104:105], 9, v[104:105]
	v_lshl_add_u64 v[102:103], v[184:185], 0, v[102:103]
	v_lshl_add_u64 v[104:105], v[184:185], 0, v[104:105]
	ds_read_b64 v[158:159], v200 offset:2048
	ds_read_b64 v[160:161], v200 offset:3072
	ds_read_b64 v[156:157], v200 offset:3328
	ds_read_b64 v[154:155], v200 offset:2304
	s_waitcnt vmcnt(2)
	v_mfma_f32_32x32x16_bf16 v[0:15], v[28:31], v[90:93], v[0:15]
	v_or_b32_e32 v28, s17, v80
	v_ashrrev_i32_e32 v104, 2, v28
	v_cndmask_b32_e64 v28, v104, 0, s[36:37]
	v_ashrrev_i32_e32 v29, 31, v28
	v_readlane_b32 s40, v252, 5
	v_readlane_b32 s41, v252, 6
	v_readlane_b32 s42, v252, 7
	s_waitcnt vmcnt(0)
	v_mfma_f32_32x32x16_bf16 v[0:15], v[24:27], v[166:169], v[0:15]
	v_or_b32_e32 v26, 2, v104
	v_cndmask_b32_e64 v26, v26, 0, s[36:37]
	v_ashrrev_i32_e32 v27, 31, v26
	v_lshlrev_b64 v[24:25], 9, v[28:29]
	v_lshlrev_b64 v[26:27], 9, v[26:27]
	v_lshl_add_u64 v[24:25], v[184:185], 0, v[24:25]
	v_lshl_add_u64 v[26:27], v[184:185], 0, v[26:27]
	s_waitcnt vmcnt(0)
	v_mfma_f32_32x32x16_bf16 v[0:15], v[16:19], v[162:165], v[0:15]
	v_or_b32_e32 v16, 4, v104
	ds_read_b64 v[150:151], v200 offset:4096
	ds_read_b64 v[152:153], v200 offset:5120
	ds_read_b64 v[148:149], v200 offset:5376
	ds_read_b64 v[146:147], v200 offset:4352
	v_cndmask_b32_e64 v102, v16, 0, s[36:37]
	v_or_b32_e32 v104, 6, v104
	v_cndmask_b32_e64 v104, v104, 0, s[36:37]
	v_ashrrev_i32_e32 v103, 31, v102
	v_ashrrev_i32_e32 v105, 31, v104
	s_waitcnt vmcnt(0)
	v_mfma_f32_32x32x16_bf16 v[16:31], v[20:23], v[32:35], 0
	v_lshlrev_b64 v[102:103], 9, v[102:103]
	v_lshlrev_b64 v[104:105], 9, v[104:105]
	v_lshl_add_u64 v[102:103], v[184:185], 0, v[102:103]
	v_lshl_add_u64 v[104:105], v[184:185], 0, v[104:105]
	ds_read_b64 v[142:143], v200 offset:6144
	ds_read_b64 v[144:145], v200 offset:7168
	ds_read_b64 v[140:141], v200 offset:7424
	ds_read_b64 v[138:139], v200 offset:6400
	v_readlane_b32 s43, v252, 8
	s_waitcnt vmcnt(0)
	v_mfma_f32_32x32x16_bf16 v[16:31], v[76:79], v[90:93], v[16:31]
	v_or_b32_e32 v76, s16, v80
	v_ashrrev_i32_e32 v104, 2, v76
	v_cndmask_b32_e64 v76, v104, 0, s[8:9]
	v_ashrrev_i32_e32 v77, 31, v76
	s_waitcnt vmcnt(0)
	v_mfma_f32_32x32x16_bf16 v[16:31], v[72:75], v[166:169], v[16:31]
	v_or_b32_e32 v74, 2, v104
	v_cndmask_b32_e64 v74, v74, 0, s[8:9]
	v_ashrrev_i32_e32 v75, 31, v74
	v_lshlrev_b64 v[72:73], 9, v[76:77]
	v_lshlrev_b64 v[74:75], 9, v[74:75]
	v_lshl_add_u64 v[72:73], v[184:185], 0, v[72:73]
	s_waitcnt vmcnt(0)
	v_mfma_f32_32x32x16_bf16 v[16:31], v[64:67], v[162:165], v[16:31]
	v_lshl_add_u64 v[64:65], v[184:185], 0, v[74:75]
	ds_read_b64 v[134:135], v200 offset:8192
	ds_read_b64 v[136:137], v200 offset:9216
	ds_read_b64 v[132:133], v200 offset:9472
	ds_read_b64 v[130:131], v200 offset:8448
	v_or_b32_e32 v64, 4, v104
	v_cndmask_b32_e64 v102, v64, 0, s[8:9]
	v_or_b32_e32 v104, 6, v104
	v_cndmask_b32_e64 v104, v104, 0, s[8:9]
	v_ashrrev_i32_e32 v103, 31, v102
	s_waitcnt vmcnt(0)
	v_mfma_f32_32x32x16_bf16 v[64:79], v[68:71], v[32:35], 0
	v_ashrrev_i32_e32 v105, 31, v104
	v_lshlrev_b64 v[102:103], 9, v[102:103]
	v_lshlrev_b64 v[104:105], 9, v[104:105]
	v_lshl_add_u64 v[102:103], v[184:185], 0, v[102:103]
	s_waitcnt vmcnt(0)
	v_mfma_f32_32x32x16_bf16 v[64:79], v[60:63], v[90:93], v[64:79]
	v_lshl_add_u64 v[60:61], v[184:185], 0, v[104:105]
	ds_read_b64 v[126:127], v200 offset:10240
	ds_read_b64 v[128:129], v200 offset:11264
	ds_read_b64 v[124:125], v200 offset:11520
	ds_read_b64 v[122:123], v200 offset:10496
	v_or_b32_e32 v60, s15, v80
	v_ashrrev_i32_e32 v104, 2, v60
	v_or_b32_e32 v102, 4, v104
	v_cndmask_b32_e64 v102, v102, 0, s[4:5]
	v_ashrrev_i32_e32 v103, 31, v102
	s_waitcnt vmcnt(0)
	v_mfma_f32_32x32x16_bf16 v[64:79], v[56:59], v[166:169], v[64:79]
	v_or_b32_e32 v58, 2, v104
	v_cndmask_b32_e64 v56, v104, 0, s[4:5]
	v_cndmask_b32_e64 v58, v58, 0, s[4:5]
	v_ashrrev_i32_e32 v57, 31, v56
	v_ashrrev_i32_e32 v59, 31, v58
	v_lshlrev_b64 v[56:57], 9, v[56:57]
	v_lshlrev_b64 v[58:59], 9, v[58:59]
	s_waitcnt vmcnt(0)
	v_mfma_f32_32x32x16_bf16 v[64:79], v[48:51], v[162:165], v[64:79]
	v_lshl_add_u64 v[48:49], v[184:185], 0, v[56:57]
	v_lshl_add_u64 v[50:51], v[184:185], 0, v[58:59]
	ds_read_b64 v[118:119], v200 offset:12288
	ds_read_b64 v[120:121], v200 offset:13312
	ds_read_b64 v[116:117], v200 offset:13568
	ds_read_b64 v[114:115], v200 offset:12544
	v_or_b32_e32 v104, 6, v104
	v_cndmask_b32_e64 v104, v104, 0, s[4:5]
	v_lshlrev_b64 v[102:103], 9, v[102:103]
	v_ashrrev_i32_e32 v105, 31, v104
	s_waitcnt vmcnt(0)
; __device__ __forceinline__ int crow(int reg, int h) { return (reg & 3) + 8 * (reg >> 2) + 4 * h; }
; #define MFMA32(a, b, c) __builtin_amdgcn_mfma_f32_32x32x16_bf16((a), (b), (c), 0, 0, 0)
; __device__ __forceinline__ void attn_prompt_wave(const Params& P, int l, int qt, int tid_in) {
;     ...
;     f32x16 st[5];
; #pragma unroll
;     for (int kb = 0; kb < 5; ++kb) {
; #pragma unroll
;         for (int i = 0; i < 16; ++i) st[kb][i] = 0.f;
; #pragma unroll
;         for (int kk = 0; kk < 4; ++kk) st[kb] = MFMA32(kf[kb][kk], qf[kk], st[kb]);
;     }
;     const int qi = q0 + l32, bstart = (qi / LP) * LP;
;     const float sink = P.in[I_SINK][l * 8 + head];
;     float mx = sink;
;     const bool interior = key0 >= (q0 / LP) * LP && (q0 + 31) / LP == q0 / LP;
; #pragma unroll
;     for (int kb = 0; kb < 5; ++kb) {
;         if (kb >= 1 && kb <= 3 && interior) {
; #pragma unroll
;             for (int i = 0; i < 16; ++i) mx = fmaxf(mx, st[kb][i]);
;         } else {
; #pragma unroll
;             for (int i = 0; i < 16; ++i) { const int ki = key0 + kb * 32 + crow(i, h); const bool ok = ki <= qi && ki > qi - 128 && ki >= bstart;
;                 st[kb][i] = ok ? st[kb][i] : -1e30f; mx = fmaxf(mx, st[kb][i]); }
;         }
	v_mfma_f32_32x32x16_bf16 v[48:63], v[52:55], v[32:35], 0
	v_lshlrev_b64 v[104:105], 9, v[104:105]
	s_waitcnt vmcnt(0)
	v_mfma_f32_32x32x16_bf16 v[48:63], v[98:101], v[90:93], v[48:63]
	v_lshl_add_u64 v[98:99], v[184:185], 0, v[102:103]
	v_lshl_add_u64 v[100:101], v[184:185], 0, v[104:105]
	ds_read_b64 v[110:111], v200 offset:14336
	ds_read_b64 v[112:113], v200 offset:15360
	ds_read_b64 v[108:109], v200 offset:15616
	ds_read_b64 v[106:107], v200 offset:14592
	v_or_b32_e32 v98, s0, v80
	v_ashrrev_i32_e32 v188, 2, v98
	v_or_b32_e32 v186, 4, v188
	v_cndmask_b32_e64 v186, v186, 0, s[2:3]
	s_waitcnt vmcnt(0)
	v_mfma_f32_32x32x16_bf16 v[48:63], v[44:47], v[166:169], v[48:63]
	v_or_b32_e32 v46, 2, v188
	v_cndmask_b32_e64 v44, v188, 0, s[2:3]
	v_cndmask_b32_e64 v46, v46, 0, s[2:3]
	v_ashrrev_i32_e32 v45, 31, v44
	v_ashrrev_i32_e32 v47, 31, v46
	v_lshlrev_b64 v[44:45], 9, v[44:45]
	v_or_b32_e32 v188, 6, v188
	s_waitcnt vmcnt(0)
	v_mfma_f32_32x32x16_bf16 v[48:63], v[36:39], v[162:165], v[48:63]
	v_lshlrev_b64 v[36:37], 9, v[46:47]
	v_lshl_add_u64 v[38:39], v[184:185], 0, v[44:45]
	v_lshl_add_u64 v[36:37], v[184:185], 0, v[36:37]
	ds_read_b64 v[102:103], v200 offset:16384
	ds_read_b64 v[104:105], v200 offset:17408
	ds_read_b64 v[100:101], v200 offset:17664
	ds_read_b64 v[98:99], v200 offset:16640
	v_cndmask_b32_e64 v188, v188, 0, s[2:3]
	v_ashrrev_i32_e32 v187, 31, v186
	v_ashrrev_i32_e32 v189, 31, v188
	s_waitcnt vmcnt(0)
	v_mfma_f32_32x32x16_bf16 v[32:47], v[40:43], v[32:35], 0
	v_lshlrev_b64 v[186:187], 9, v[186:187]
	v_lshl_add_u64 v[186:187], v[184:185], 0, v[186:187]
	s_mul_hi_i32 s2, s0, 0xfe03f81
	s_lshr_b32 s3, s2, 31
	s_ashr_i32 s4, s2, 7
	s_add_i32 s4, s4, s3
	s_mul_i32 s2, s4, 0x810
	s_waitcnt vmcnt(0)
	v_mfma_f32_32x32x16_bf16 v[32:47], v[94:97], v[90:93], v[32:47]
	v_lshlrev_b64 v[90:91], 9, v[188:189]
	v_lshl_add_u64 v[90:91], v[184:185], 0, v[90:91]
	ds_read_b64 v[94:95], v200 offset:18432
	ds_read_b64 v[96:97], v200 offset:19456
	ds_read_b64 v[92:93], v200 offset:19712
	s_nop 0
	ds_read_b64 v[90:91], v200 offset:18688
	s_cmp_lt_i32 s1, s2
	s_mov_b64 s[2:3], 0
	s_waitcnt vmcnt(0)
	v_mfma_f32_32x32x16_bf16 v[32:47], v[174:177], v[166:169], v[32:47]
	v_add_u32_e32 v166, s13, v190
	v_ashrrev_i32_e32 v167, 31, v166
	v_lshl_add_u64 v[166:167], v[166:167], 2, s[54:55]
	global_load_dword v166, v[166:167], off
	s_waitcnt vmcnt(1)
	v_mfma_f32_32x32x16_bf16 v[32:47], v[170:173], v[162:165], v[32:47]
	s_cbranch_scc1 .LBB0_1022
	s_or_b32 s0, s0, 31
	s_mul_hi_i32 s0, s0, 0xfe03f81
	s_lshr_b32 s1, s0, 31
	s_ashr_i32 s0, s0, 7
	s_add_i32 s0, s0, s1
	s_cmp_eq_u32 s0, s4
	s_cselect_b64 s[2:3], -1, 0
.LBB0_1022:
	v_mul_hi_i32 v162, v182, s71
	v_lshrrev_b32_e32 v163, 31, v162
	v_ashrrev_i32_e32 v162, 7, v162
	v_add_u32_e32 v162, v162, v163
	v_add_u32_e32 v190, 0xffffff80, v182
	v_mul_lo_u32 v185, v162, s73
	v_cmp_le_i32_e32 vcc, v183, v182
	v_cmp_gt_i32_e64 s[36:37], v183, v190
	s_and_b64 s[0:1], vcc, s[36:37]
	v_cmp_ge_i32_e32 vcc, v183, v185
	s_and_b64 vcc, s[0:1], vcc
	v_cmp_ge_i32_e64 s[36:37], v183, v190
	v_cndmask_b32_e32 v184, v233, v0, vcc
	v_or_b32_e32 v0, 1, v183
	v_cmp_ge_i32_e64 s[38:39], v0, v185
	v_cmp_lt_i32_e32 vcc, v183, v182
	s_and_b64 s[0:1], s[36:37], s[38:39]
	s_and_b64 vcc, s[0:1], vcc
	v_cndmask_b32_e32 v171, v233, v1, vcc
	v_or_b32_e32 v1, 2, v183
	v_cmp_le_i32_e32 vcc, v1, v182
	v_cmp_gt_i32_e64 s[36:37], v1, v190
	s_and_b64 s[0:1], vcc, s[36:37]
	v_cmp_ge_i32_e32 vcc, v1, v185
	s_and_b64 vcc, s[0:1], vcc
	v_or_b32_e32 v1, 3, v183
	v_cndmask_b32_e32 v177, v233, v2, vcc
	v_cmp_le_i32_e32 vcc, v1, v182
	v_cmp_gt_i32_e64 s[36:37], v1, v190
	s_and_b64 s[0:1], vcc, s[36:37]
	v_cmp_ge_i32_e32 vcc, v1, v185
	s_and_b64 vcc, s[0:1], vcc
	v_or_b32_e32 v1, 8, v183
	v_cndmask_b32_e32 v169, v233, v3, vcc
	v_cmp_le_i32_e32 vcc, v1, v182
	v_cmp_gt_i32_e64 s[36:37], v1, v190
	s_and_b64 s[0:1], vcc, s[36:37]
	v_cmp_ge_i32_e32 vcc, v1, v185
	s_and_b64 vcc, s[0:1], vcc
	v_or_b32_e32 v1, 9, v183
	v_cndmask_b32_e32 v176, v233, v4, vcc
	v_cmp_le_i32_e32 vcc, v1, v182
	v_cmp_gt_i32_e64 s[36:37], v1, v190
	s_and_b64 s[0:1], vcc, s[36:37]
	v_cmp_ge_i32_e32 vcc, v1, v185
	s_and_b64 vcc, s[0:1], vcc
	v_or_b32_e32 v1, 10, v183
	v_cndmask_b32_e32 v168, v233, v5, vcc
	v_cmp_le_i32_e32 vcc, v1, v182
	v_cmp_gt_i32_e64 s[36:37], v1, v190
	s_and_b64 s[0:1], vcc, s[36:37]
	v_cmp_ge_i32_e32 vcc, v1, v185
	s_and_b64 vcc, s[0:1], vcc
	v_or_b32_e32 v1, 11, v183
	v_cndmask_b32_e32 v175, v233, v6, vcc
	v_cmp_le_i32_e32 vcc, v1, v182
	v_cmp_gt_i32_e64 s[36:37], v1, v190
	s_and_b64 s[0:1], vcc, s[36:37]
	v_cmp_ge_i32_e32 vcc, v1, v185
	s_and_b64 vcc, s[0:1], vcc
	v_or_b32_e32 v1, 16, v183
	v_cndmask_b32_e32 v167, v233, v7, vcc
	v_cmp_le_i32_e32 vcc, v1, v182
	v_cmp_gt_i32_e64 s[36:37], v1, v190
	s_and_b64 s[0:1], vcc, s[36:37]
	v_cmp_ge_i32_e32 vcc, v1, v185
	s_and_b64 vcc, s[0:1], vcc
	v_or_b32_e32 v1, 17, v183
	v_cndmask_b32_e32 v174, v233, v8, vcc
	v_cmp_le_i32_e32 vcc, v1, v182
	v_cmp_gt_i32_e64 s[36:37], v1, v190
	s_and_b64 s[0:1], vcc, s[36:37]
	v_cmp_ge_i32_e32 vcc, v1, v185
	s_and_b64 vcc, s[0:1], vcc
	v_or_b32_e32 v1, 18, v183
	v_cndmask_b32_e32 v165, v233, v9, vcc
	v_cmp_le_i32_e32 vcc, v1, v182
	v_cmp_gt_i32_e64 s[36:37], v1, v190
	s_and_b64 s[0:1], vcc, s[36:37]
	v_cmp_ge_i32_e32 vcc, v1, v185
	s_and_b64 vcc, s[0:1], vcc
	v_or_b32_e32 v1, 19, v183
	v_cndmask_b32_e32 v173, v233, v10, vcc
	v_cmp_le_i32_e32 vcc, v1, v182
	v_cmp_gt_i32_e64 s[36:37], v1, v190
	s_and_b64 s[0:1], vcc, s[36:37]
	v_cmp_ge_i32_e32 vcc, v1, v185
	s_and_b64 vcc, s[0:1], vcc
	v_or_b32_e32 v1, 24, v183
	v_cndmask_b32_e32 v164, v233, v11, vcc
	v_cmp_le_i32_e32 vcc, v1, v182
	v_cmp_gt_i32_e64 s[36:37], v1, v190
	s_and_b64 s[0:1], vcc, s[36:37]
	v_cmp_ge_i32_e32 vcc, v1, v185
	s_and_b64 vcc, s[0:1], vcc
	v_or_b32_e32 v1, 25, v183
	v_cndmask_b32_e32 v172, v233, v12, vcc
	v_cmp_le_i32_e32 vcc, v1, v182
	v_cmp_gt_i32_e64 s[36:37], v1, v190
	s_and_b64 s[0:1], vcc, s[36:37]
	v_cmp_ge_i32_e32 vcc, v1, v185
	s_and_b64 vcc, s[0:1], vcc
	v_or_b32_e32 v1, 26, v183
	s_waitcnt vmcnt(0) lgkmcnt(0)
	s_barrier
; __device__ __forceinline__ int crow(int reg, int h) { return (reg & 3) + 8 * (reg >> 2) + 4 * h; }
; __device__ __forceinline__ void attn_prompt_wave(const Params& P, int l, int qt, int tid_in) {
;     ...
; #pragma unroll
;     for (int kb = 0; kb < 5; ++kb) {
;         if (kb >= 1 && kb <= 3 && interior) {
; #pragma unroll
;             for (int i = 0; i < 16; ++i) mx = fmaxf(mx, st[kb][i]);
;         } else {
; #pragma unroll
;             for (int i = 0; i < 16; ++i) { const int ki = key0 + kb * 32 + crow(i, h); const bool ok = ki <= qi && ki > qi - 128 && ki >= bstart;
;                 st[kb][i] = ok ? st[kb][i] : -1e30f; mx = fmaxf(mx, st[kb][i]); }
;         }
;     }
	v_max3_f32 v0, v166, v184, v171
	v_cndmask_b32_e32 v163, v233, v13, vcc
	v_cmp_le_i32_e32 vcc, v1, v182
	v_cmp_gt_i32_e64 s[36:37], v1, v190
	v_max3_f32 v0, v0, v177, v169
	s_and_b64 s[0:1], vcc, s[36:37]
	v_cmp_ge_i32_e32 vcc, v1, v185
	v_max3_f32 v0, v0, v176, v168
	s_and_b64 vcc, s[0:1], vcc
	v_or_b32_e32 v1, 27, v183
	v_max3_f32 v0, v0, v175, v167
	v_cndmask_b32_e32 v170, v233, v14, vcc
	v_cmp_le_i32_e32 vcc, v1, v182
	v_cmp_gt_i32_e64 s[36:37], v1, v190
	v_max3_f32 v0, v0, v174, v165
	s_and_b64 s[0:1], vcc, s[36:37]
	v_cmp_ge_i32_e32 vcc, v1, v185
	v_max3_f32 v0, v0, v173, v164
	s_and_b64 vcc, s[0:1], vcc
	v_max3_f32 v0, v0, v172, v163
	v_cndmask_b32_e32 v162, v233, v15, vcc
	s_mov_b64 s[4:5], -1
	v_max3_f32 v191, v0, v170, v162
	s_and_b64 vcc, exec, s[2:3]
	s_cbranch_vccnz .LBB0_1024
	v_add_u32_e32 v15, 32, v183
	v_cmp_le_i32_e32 vcc, v15, v182
	v_cmp_gt_i32_e64 s[36:37], v15, v190
	s_and_b64 s[0:1], vcc, s[36:37]
	v_cmp_ge_i32_e32 vcc, v15, v185
	v_or_b32_e32 v1, 1, v15
	s_and_b64 vcc, s[0:1], vcc
	v_cmp_ge_i32_e64 s[36:37], v15, v190
	v_cmp_ge_i32_e64 s[38:39], v1, v185
	v_cndmask_b32_e32 v0, v233, v16, vcc
	v_cmp_lt_i32_e32 vcc, v15, v182
	s_and_b64 s[0:1], s[36:37], s[38:39]
	s_and_b64 vcc, s[0:1], vcc
	v_or_b32_e32 v2, 2, v15
	v_cndmask_b32_e32 v1, v233, v17, vcc
	v_cmp_le_i32_e32 vcc, v2, v182
	v_cmp_gt_i32_e64 s[36:37], v2, v190
	s_and_b64 s[0:1], vcc, s[36:37]
	v_cmp_ge_i32_e32 vcc, v2, v185
	s_and_b64 vcc, s[0:1], vcc
	v_or_b32_e32 v3, 3, v15
	v_cndmask_b32_e32 v2, v233, v18, vcc
	v_cmp_le_i32_e32 vcc, v3, v182
	v_cmp_gt_i32_e64 s[36:37], v3, v190
	s_and_b64 s[0:1], vcc, s[36:37]
	v_cmp_ge_i32_e32 vcc, v3, v185
	s_and_b64 vcc, s[0:1], vcc
	v_max3_f32 v4, v191, v0, v1
	v_cndmask_b32_e32 v3, v233, v19, vcc
	v_max3_f32 v6, v4, v2, v3
	v_or_b32_e32 v4, 8, v15
	v_cmp_le_i32_e32 vcc, v4, v182
	v_cmp_gt_i32_e64 s[36:37], v4, v190
	s_and_b64 s[0:1], vcc, s[36:37]
	v_cmp_ge_i32_e32 vcc, v4, v185
	s_and_b64 vcc, s[0:1], vcc
	v_or_b32_e32 v5, 9, v15
	v_cndmask_b32_e32 v4, v233, v20, vcc
	v_cmp_le_i32_e32 vcc, v5, v182
	v_cmp_gt_i32_e64 s[36:37], v5, v190
	s_and_b64 s[0:1], vcc, s[36:37]
	v_cmp_ge_i32_e32 vcc, v5, v185
	s_and_b64 vcc, s[0:1], vcc
	v_or_b32_e32 v7, 11, v15
	v_cndmask_b32_e32 v5, v233, v21, vcc
	v_max3_f32 v8, v6, v4, v5
	v_or_b32_e32 v6, 10, v15
	v_cmp_le_i32_e32 vcc, v6, v182
	v_cmp_gt_i32_e64 s[36:37], v6, v190
	s_and_b64 s[0:1], vcc, s[36:37]
	v_cmp_ge_i32_e32 vcc, v6, v185
	s_and_b64 vcc, s[0:1], vcc
	v_cmp_gt_i32_e64 s[36:37], v7, v190
	v_cndmask_b32_e32 v6, v233, v22, vcc
	v_cmp_le_i32_e32 vcc, v7, v182
	s_and_b64 s[0:1], vcc, s[36:37]
	v_cmp_ge_i32_e32 vcc, v7, v185
	s_and_b64 vcc, s[0:1], vcc
	v_or_b32_e32 v9, 17, v15
	v_cndmask_b32_e32 v7, v233, v23, vcc
	v_max3_f32 v10, v8, v6, v7
	v_or_b32_e32 v8, 16, v15
	v_cmp_le_i32_e32 vcc, v8, v182
	v_cmp_gt_i32_e64 s[36:37], v8, v190
	s_and_b64 s[0:1], vcc, s[36:37]
	v_cmp_ge_i32_e32 vcc, v8, v185
	s_and_b64 vcc, s[0:1], vcc
	v_cmp_gt_i32_e64 s[36:37], v9, v190
	v_cndmask_b32_e32 v8, v233, v24, vcc
	v_cmp_le_i32_e32 vcc, v9, v182
	s_and_b64 s[0:1], vcc, s[36:37]
	v_cmp_ge_i32_e32 vcc, v9, v185
	s_and_b64 vcc, s[0:1], vcc
	v_or_b32_e32 v11, 19, v15
	v_cndmask_b32_e32 v9, v233, v25, vcc
	v_max3_f32 v12, v10, v8, v9
	v_or_b32_e32 v10, 18, v15
	v_cmp_le_i32_e32 vcc, v10, v182
	v_cmp_gt_i32_e64 s[36:37], v10, v190
	s_and_b64 s[0:1], vcc, s[36:37]
	v_cmp_ge_i32_e32 vcc, v10, v185
	s_and_b64 vcc, s[0:1], vcc
	v_cmp_gt_i32_e64 s[36:37], v11, v190
	v_cndmask_b32_e32 v10, v233, v26, vcc
	v_cmp_le_i32_e32 vcc, v11, v182
	s_and_b64 s[0:1], vcc, s[36:37]
	v_cmp_ge_i32_e32 vcc, v11, v185
	s_and_b64 vcc, s[0:1], vcc
	v_or_b32_e32 v13, 25, v15
	v_cndmask_b32_e32 v11, v233, v27, vcc
	v_max3_f32 v14, v12, v10, v11
	v_or_b32_e32 v12, 24, v15
	v_cmp_le_i32_e32 vcc, v12, v182
	v_cmp_gt_i32_e64 s[36:37], v12, v190
	s_and_b64 s[0:1], vcc, s[36:37]
	v_cmp_ge_i32_e32 vcc, v12, v185
	s_and_b64 vcc, s[0:1], vcc
	v_cmp_gt_i32_e64 s[36:37], v13, v190
	v_cndmask_b32_e32 v12, v233, v28, vcc
	v_cmp_le_i32_e32 vcc, v13, v182
	s_and_b64 s[0:1], vcc, s[36:37]
	v_cmp_ge_i32_e32 vcc, v13, v185
	s_and_b64 vcc, s[0:1], vcc
	s_mov_b64 s[4:5], 0
	v_cndmask_b32_e32 v13, v233, v29, vcc
	v_max3_f32 v186, v14, v12, v13
	v_or_b32_e32 v14, 26, v15
	v_cmp_le_i32_e32 vcc, v14, v182
	v_cmp_gt_i32_e64 s[36:37], v14, v190
	s_and_b64 s[0:1], vcc, s[36:37]
	v_cmp_ge_i32_e32 vcc, v14, v185
	s_and_b64 vcc, s[0:1], vcc
	v_or_b32_e32 v15, 27, v15
	v_cndmask_b32_e32 v14, v233, v30, vcc
	v_cmp_le_i32_e32 vcc, v15, v182
	v_cmp_gt_i32_e64 s[36:37], v15, v190
	s_and_b64 s[0:1], vcc, s[36:37]
	v_cmp_ge_i32_e32 vcc, v15, v185
	s_and_b64 vcc, s[0:1], vcc
	s_nop 0
	v_cndmask_b32_e32 v15, v233, v31, vcc
	v_max3_f32 v192, v186, v14, v15
